# v38 plus prologue modulation GEMV loop with 16 weight loads in flight per thread (was 4 loads then a full wait per iteration)
# speedup vs baseline: 1.0043x; 1.0033x over previous
; #define LAS __attribute__((address_space(3)))
; __device__ __forceinline__ f32x4 zero4v() { f32x4 z = (f32x4){0.f, 0.f, 0.f, 0.f}; asm volatile("" : "+v"(z)); return z; }
; __device__ __forceinline__ void p0_prologue(const Frame& F) {
;     ...
;         for (int u = F.bid; u < DEPTH * 192; u += F.nb) {
;             const int l = u / 192, cb = (u % 192) * 64;
;             const float* wp = F.in[I_ADAW] + (size_t)l * D * (6 * D) + cb + cg * 4;
;             f32x4 a0 = zero4v(), a1 = a0;
; #pragma unroll 4
;             for (int k = ks; k < D; k += 32) { const f32x4 w = *(const f32x4*)(wp + (size_t)k * (6 * D)); a0 += w * sv[k]; a1 += w * sv[D + k]; }
;             LAS float* rp = red + (ks * 16 + cg) * 8;
; #pragma unroll
;             for (int j = 0; j < 4; ++j) { rp[j] = a0[j]; rp[4 + j] = a1[j]; }
.LBB0_84:
	v_lshl_add_u64 v[34:35], v[26:27], 0, s[22:23]
	v_lshl_add_u64 v[40:41], v[24:25], 0, s[22:23]
	v_lshl_add_u64 v[52:53], v[14:15], 0, s[22:23]
	v_lshl_add_u64 v[48:49], v[16:17], 0, s[22:23]
	global_load_dwordx4 v[34:37], v[34:35], off
	s_nop 0
	global_load_dwordx4 v[40:43], v[40:41], off
	s_nop 0
	global_load_dwordx4 v[48:51], v[48:49], off
	s_nop 0
	global_load_dwordx4 v[52:55], v[52:53], off
	v_lshl_add_u64 v[14:15], v[14:15], 0, s[14:15]
	v_lshl_add_u64 v[16:17], v[16:17], 0, s[14:15]
	v_lshl_add_u64 v[24:25], v[24:25], 0, s[14:15]
	v_lshl_add_u64 v[26:27], v[26:27], 0, s[14:15]
	v_lshl_add_u64 v[152:153], v[26:27], 0, s[22:23]
	v_lshl_add_u64 v[156:157], v[24:25], 0, s[22:23]
	v_lshl_add_u64 v[164:165], v[14:15], 0, s[22:23]
	v_lshl_add_u64 v[160:161], v[16:17], 0, s[22:23]
	global_load_dwordx4 v[152:155], v[152:153], off
	s_nop 0
	global_load_dwordx4 v[156:159], v[156:157], off
	s_nop 0
	global_load_dwordx4 v[160:163], v[160:161], off
	s_nop 0
	global_load_dwordx4 v[164:167], v[164:165], off
	v_lshl_add_u64 v[14:15], v[14:15], 0, s[14:15]
	v_lshl_add_u64 v[16:17], v[16:17], 0, s[14:15]
	v_lshl_add_u64 v[24:25], v[24:25], 0, s[14:15]
	v_lshl_add_u64 v[26:27], v[26:27], 0, s[14:15]
	v_lshl_add_u64 v[204:205], v[26:27], 0, s[22:23]
	v_lshl_add_u64 v[208:209], v[24:25], 0, s[22:23]
	v_lshl_add_u64 v[216:217], v[14:15], 0, s[22:23]
	v_lshl_add_u64 v[212:213], v[16:17], 0, s[22:23]
	global_load_dwordx4 v[204:207], v[204:205], off
	s_nop 0
	global_load_dwordx4 v[208:211], v[208:209], off
	s_nop 0
	global_load_dwordx4 v[212:215], v[212:213], off
	s_nop 0
	global_load_dwordx4 v[216:219], v[216:217], off
	v_lshl_add_u64 v[14:15], v[14:15], 0, s[14:15]
	v_lshl_add_u64 v[16:17], v[16:17], 0, s[14:15]
	v_lshl_add_u64 v[24:25], v[24:25], 0, s[14:15]
	v_lshl_add_u64 v[26:27], v[26:27], 0, s[14:15]
	v_lshl_add_u64 v[220:221], v[26:27], 0, s[22:23]
	v_lshl_add_u64 v[224:225], v[24:25], 0, s[22:23]
	v_lshl_add_u64 v[232:233], v[14:15], 0, s[22:23]
	v_lshl_add_u64 v[228:229], v[16:17], 0, s[22:23]
	global_load_dwordx4 v[220:223], v[220:221], off
	s_nop 0
	global_load_dwordx4 v[224:227], v[224:225], off
	s_nop 0
	global_load_dwordx4 v[228:231], v[228:229], off
	s_nop 0
	global_load_dwordx4 v[232:235], v[232:233], off
	v_lshl_add_u64 v[14:15], v[14:15], 0, s[14:15]
	v_lshl_add_u64 v[16:17], v[16:17], 0, s[14:15]
	v_lshl_add_u64 v[24:25], v[24:25], 0, s[14:15]
	v_lshl_add_u64 v[26:27], v[26:27], 0, s[14:15]
	ds_read2_b32 v[44:45], v33 offset1:32
	v_add_u32_e32 v47, 0x2000, v33
	ds_read2_b32 v[56:57], v33 offset0:64 offset1:96
	ds_read2_b32 v[58:59], v47 offset1:32
	ds_read2_b32 v[60:61], v47 offset0:64 offset1:96
	v_add_u32_e32 v32, 0x80, v32
	s_waitcnt lgkmcnt(0)
	v_mov_b32_e32 v62, v45
	v_mov_b32_e32 v66, v59
	v_mov_b32_e32 v64, v57
	v_mov_b32_e32 v68, v61
	v_add_u32_e32 v33, 0x200, v33
	s_waitcnt vmcnt(12)
	v_pk_fma_f32 v[10:11], v[34:35], v[44:45], v[10:11] op_sel_hi:[1,0,1]
	v_pk_fma_f32 v[12:13], v[36:37], v[44:45], v[12:13] op_sel_hi:[1,0,1]
	v_pk_fma_f32 v[6:7], v[34:35], v[58:59], v[6:7] op_sel_hi:[1,0,1]
	v_pk_fma_f32 v[8:9], v[36:37], v[58:59], v[8:9] op_sel_hi:[1,0,1]
	v_pk_fma_f32 v[12:13], v[42:43], v[62:63], v[12:13] op_sel_hi:[1,0,1]
	v_pk_fma_f32 v[10:11], v[40:41], v[62:63], v[10:11] op_sel_hi:[1,0,1]
	v_pk_fma_f32 v[8:9], v[42:43], v[66:67], v[8:9] op_sel_hi:[1,0,1]
	v_pk_fma_f32 v[6:7], v[40:41], v[66:67], v[6:7] op_sel_hi:[1,0,1]
	v_pk_fma_f32 v[12:13], v[50:51], v[56:57], v[12:13] op_sel_hi:[1,0,1]
	v_pk_fma_f32 v[10:11], v[48:49], v[56:57], v[10:11] op_sel_hi:[1,0,1]
	v_pk_fma_f32 v[8:9], v[50:51], v[60:61], v[8:9] op_sel_hi:[1,0,1]
	v_pk_fma_f32 v[6:7], v[48:49], v[60:61], v[6:7] op_sel_hi:[1,0,1]
	v_pk_fma_f32 v[12:13], v[54:55], v[64:65], v[12:13] op_sel_hi:[1,0,1]
	v_pk_fma_f32 v[10:11], v[52:53], v[64:65], v[10:11] op_sel_hi:[1,0,1]
	v_pk_fma_f32 v[8:9], v[54:55], v[68:69], v[8:9] op_sel_hi:[1,0,1]
	v_pk_fma_f32 v[6:7], v[52:53], v[68:69], v[6:7] op_sel_hi:[1,0,1]
	ds_read2_b32 v[44:45], v33 offset1:32
	v_add_u32_e32 v47, 0x2000, v33
	ds_read2_b32 v[56:57], v33 offset0:64 offset1:96
	ds_read2_b32 v[58:59], v47 offset1:32
	ds_read2_b32 v[60:61], v47 offset0:64 offset1:96
	v_add_u32_e32 v32, 0x80, v32
	s_waitcnt lgkmcnt(0)
	v_mov_b32_e32 v62, v45
	v_mov_b32_e32 v66, v59
	v_mov_b32_e32 v64, v57
	v_mov_b32_e32 v68, v61
	v_add_u32_e32 v33, 0x200, v33
	s_waitcnt vmcnt(8)
; #define LAS __attribute__((address_space(3)))
; __device__ __forceinline__ f32x4 zero4v() { f32x4 z = (f32x4){0.f, 0.f, 0.f, 0.f}; asm volatile("" : "+v"(z)); return z; }
; __device__ __forceinline__ void p0_prologue(const Frame& F) {
;     ...
;         for (int u = F.bid; u < DEPTH * 192; u += F.nb) {
;             const int l = u / 192, cb = (u % 192) * 64;
;             const float* wp = F.in[I_ADAW] + (size_t)l * D * (6 * D) + cb + cg * 4;
;             f32x4 a0 = zero4v(), a1 = a0;
; #pragma unroll 4
;             for (int k = ks; k < D; k += 32) { const f32x4 w = *(const f32x4*)(wp + (size_t)k * (6 * D)); a0 += w * sv[k]; a1 += w * sv[D + k]; }
;             LAS float* rp = red + (ks * 16 + cg) * 8;
; #pragma unroll
;             for (int j = 0; j < 4; ++j) { rp[j] = a0[j]; rp[4 + j] = a1[j]; }
	v_pk_fma_f32 v[10:11], v[152:153], v[44:45], v[10:11] op_sel_hi:[1,0,1]
	v_pk_fma_f32 v[12:13], v[154:155], v[44:45], v[12:13] op_sel_hi:[1,0,1]
	v_pk_fma_f32 v[6:7], v[152:153], v[58:59], v[6:7] op_sel_hi:[1,0,1]
	v_pk_fma_f32 v[8:9], v[154:155], v[58:59], v[8:9] op_sel_hi:[1,0,1]
	v_pk_fma_f32 v[12:13], v[158:159], v[62:63], v[12:13] op_sel_hi:[1,0,1]
	v_pk_fma_f32 v[10:11], v[156:157], v[62:63], v[10:11] op_sel_hi:[1,0,1]
	v_pk_fma_f32 v[8:9], v[158:159], v[66:67], v[8:9] op_sel_hi:[1,0,1]
	v_pk_fma_f32 v[6:7], v[156:157], v[66:67], v[6:7] op_sel_hi:[1,0,1]
	v_pk_fma_f32 v[12:13], v[162:163], v[56:57], v[12:13] op_sel_hi:[1,0,1]
	v_pk_fma_f32 v[10:11], v[160:161], v[56:57], v[10:11] op_sel_hi:[1,0,1]
	v_pk_fma_f32 v[8:9], v[162:163], v[60:61], v[8:9] op_sel_hi:[1,0,1]
	v_pk_fma_f32 v[6:7], v[160:161], v[60:61], v[6:7] op_sel_hi:[1,0,1]
	v_pk_fma_f32 v[12:13], v[166:167], v[64:65], v[12:13] op_sel_hi:[1,0,1]
	v_pk_fma_f32 v[10:11], v[164:165], v[64:65], v[10:11] op_sel_hi:[1,0,1]
	v_pk_fma_f32 v[8:9], v[166:167], v[68:69], v[8:9] op_sel_hi:[1,0,1]
	v_pk_fma_f32 v[6:7], v[164:165], v[68:69], v[6:7] op_sel_hi:[1,0,1]
	ds_read2_b32 v[44:45], v33 offset1:32
	v_add_u32_e32 v47, 0x2000, v33
	ds_read2_b32 v[56:57], v33 offset0:64 offset1:96
	ds_read2_b32 v[58:59], v47 offset1:32
	ds_read2_b32 v[60:61], v47 offset0:64 offset1:96
	v_add_u32_e32 v32, 0x80, v32
	s_waitcnt lgkmcnt(0)
	v_mov_b32_e32 v62, v45
	v_mov_b32_e32 v66, v59
	v_mov_b32_e32 v64, v57
	v_mov_b32_e32 v68, v61
	v_add_u32_e32 v33, 0x200, v33
	s_waitcnt vmcnt(4)
	v_pk_fma_f32 v[10:11], v[204:205], v[44:45], v[10:11] op_sel_hi:[1,0,1]
	v_pk_fma_f32 v[12:13], v[206:207], v[44:45], v[12:13] op_sel_hi:[1,0,1]
	v_pk_fma_f32 v[6:7], v[204:205], v[58:59], v[6:7] op_sel_hi:[1,0,1]
	v_pk_fma_f32 v[8:9], v[206:207], v[58:59], v[8:9] op_sel_hi:[1,0,1]
	v_pk_fma_f32 v[12:13], v[210:211], v[62:63], v[12:13] op_sel_hi:[1,0,1]
	v_pk_fma_f32 v[10:11], v[208:209], v[62:63], v[10:11] op_sel_hi:[1,0,1]
	v_pk_fma_f32 v[8:9], v[210:211], v[66:67], v[8:9] op_sel_hi:[1,0,1]
	v_pk_fma_f32 v[6:7], v[208:209], v[66:67], v[6:7] op_sel_hi:[1,0,1]
	v_pk_fma_f32 v[12:13], v[214:215], v[56:57], v[12:13] op_sel_hi:[1,0,1]
	v_pk_fma_f32 v[10:11], v[212:213], v[56:57], v[10:11] op_sel_hi:[1,0,1]
	v_pk_fma_f32 v[8:9], v[214:215], v[60:61], v[8:9] op_sel_hi:[1,0,1]
	v_pk_fma_f32 v[6:7], v[212:213], v[60:61], v[6:7] op_sel_hi:[1,0,1]
	v_pk_fma_f32 v[12:13], v[218:219], v[64:65], v[12:13] op_sel_hi:[1,0,1]
	v_pk_fma_f32 v[10:11], v[216:217], v[64:65], v[10:11] op_sel_hi:[1,0,1]
	v_pk_fma_f32 v[8:9], v[218:219], v[68:69], v[8:9] op_sel_hi:[1,0,1]
	v_pk_fma_f32 v[6:7], v[216:217], v[68:69], v[6:7] op_sel_hi:[1,0,1]
	ds_read2_b32 v[44:45], v33 offset1:32
	v_add_u32_e32 v47, 0x2000, v33
	ds_read2_b32 v[56:57], v33 offset0:64 offset1:96
	ds_read2_b32 v[58:59], v47 offset1:32
	ds_read2_b32 v[60:61], v47 offset0:64 offset1:96
	v_add_u32_e32 v32, 0x80, v32
	s_waitcnt lgkmcnt(0)
	v_mov_b32_e32 v62, v45
	v_mov_b32_e32 v66, v59
	v_mov_b32_e32 v64, v57
	v_mov_b32_e32 v68, v61
	v_add_u32_e32 v33, 0x200, v33
	s_waitcnt vmcnt(0)
	v_pk_fma_f32 v[10:11], v[220:221], v[44:45], v[10:11] op_sel_hi:[1,0,1]
	v_pk_fma_f32 v[12:13], v[222:223], v[44:45], v[12:13] op_sel_hi:[1,0,1]
	v_pk_fma_f32 v[6:7], v[220:221], v[58:59], v[6:7] op_sel_hi:[1,0,1]
	v_pk_fma_f32 v[8:9], v[222:223], v[58:59], v[8:9] op_sel_hi:[1,0,1]
	v_pk_fma_f32 v[12:13], v[226:227], v[62:63], v[12:13] op_sel_hi:[1,0,1]
	v_pk_fma_f32 v[10:11], v[224:225], v[62:63], v[10:11] op_sel_hi:[1,0,1]
	v_pk_fma_f32 v[8:9], v[226:227], v[66:67], v[8:9] op_sel_hi:[1,0,1]
	v_pk_fma_f32 v[6:7], v[224:225], v[66:67], v[6:7] op_sel_hi:[1,0,1]
	v_pk_fma_f32 v[12:13], v[230:231], v[56:57], v[12:13] op_sel_hi:[1,0,1]
	v_pk_fma_f32 v[10:11], v[228:229], v[56:57], v[10:11] op_sel_hi:[1,0,1]
	v_pk_fma_f32 v[8:9], v[230:231], v[60:61], v[8:9] op_sel_hi:[1,0,1]
	v_pk_fma_f32 v[6:7], v[228:229], v[60:61], v[6:7] op_sel_hi:[1,0,1]
	v_pk_fma_f32 v[12:13], v[234:235], v[64:65], v[12:13] op_sel_hi:[1,0,1]
	v_pk_fma_f32 v[10:11], v[232:233], v[64:65], v[10:11] op_sel_hi:[1,0,1]
	v_pk_fma_f32 v[8:9], v[234:235], v[68:69], v[8:9] op_sel_hi:[1,0,1]
	v_pk_fma_f32 v[6:7], v[232:233], v[68:69], v[6:7] op_sel_hi:[1,0,1]
	v_cmp_lt_i32_e64 s[8:9], s3, v32
	s_or_b64 s[24:25], s[8:9], s[24:25]
	s_andn2_b64 exec, exec, s[24:25]
	s_cbranch_execnz .LBB0_84
	s_nop 0
	s_nop 0
	s_nop 0
	s_nop 0
	s_nop 0
	s_nop 0
	s_nop 0
	s_nop 0
	s_or_b64 exec, exec, s[24:25]
